# final RMSNorm of the sample rows (P11): the gain loads issued with the row loads instead of one serial store-ack plus load per 1 KiB chunk
# baseline (speedup 1.0000x reference)
.LBB0_1360:
	global_load_dwordx4 v[12:15], v[2:3], off offset:-2048 nt
	global_load_dwordx4 v[16:19], v[2:3], off offset:-1024 nt
	global_load_dwordx4 v[20:23], v[2:3], off offset:1024 nt
	global_load_dwordx4 v[24:27], v[2:3], off nt
	global_load_dwordx4 v[28:31], v[0:1], off
	global_load_dwordx4 v[48:51], v[0:1], off offset:1024
	global_load_dwordx4 v[52:55], v[0:1], off offset:2048
	global_load_dwordx4 v[56:59], v[0:1], off offset:3072
	s_add_i32 s0, s0, s4
	s_cmpk_lt_i32 s0, 0x4100
	s_waitcnt vmcnt(0)
	v_pk_mul_f32 v[32:33], v[14:15], v[14:15]
	v_pk_mul_f32 v[34:35], v[12:13], v[12:13]
	v_pk_mul_f32 v[36:37], v[18:19], v[18:19]
	v_pk_mul_f32 v[38:39], v[16:17], v[16:17]
	v_pk_mov_b32 v[44:45], v[34:35], v[32:33] op_sel:[1,0]
	v_mov_b32_e32 v35, v33
	v_pk_mov_b32 v[32:33], v[38:39], v[36:37] op_sel:[1,0]
	v_mov_b32_e32 v39, v37
	v_mul_f32_e32 v43, v21, v21
	v_mul_f32_e32 v40, v25, v25
	v_mul_f32_e32 v42, v27, v27
	v_pk_add_f32 v[34:35], v[44:45], v[34:35]
	v_pk_add_f32 v[32:33], v[32:33], v[38:39]
	v_mul_f32_e32 v11, v20, v20
	v_mul_f32_e32 v46, v22, v22
	v_mul_f32_e32 v47, v23, v23
	v_pk_fma_f32 v[36:37], v[24:25], v[24:25], v[40:41] op_sel_hi:[1,1,0]
	v_pk_fma_f32 v[40:41], v[26:27], v[26:27], v[42:43] op_sel_hi:[1,1,0]
	v_pk_add_f32 v[34:35], v[34:35], v[34:35] op_sel:[0,1] op_sel_hi:[1,0]
	v_pk_add_f32 v[32:33], v[32:33], v[32:33] op_sel:[0,1] op_sel_hi:[1,0]
	v_mov_b32_e32 v37, v46
	v_mov_b32_e32 v41, v47
	v_mov_b32_e32 v35, v11
	v_mov_b32_e32 v33, v43
	v_pk_add_f32 v[36:37], v[36:37], v[40:41]
	v_pk_add_f32 v[32:33], v[34:35], v[32:33]
	s_nop 0
	v_pk_add_f32 v[32:33], v[32:33], v[36:37]
	s_nop 0
	v_add_f32_e32 v11, v32, v33
	ds_bpermute_b32 v32, v4, v11
	s_waitcnt lgkmcnt(0)
	v_add_f32_e32 v11, v11, v32
	ds_bpermute_b32 v32, v5, v11
	s_waitcnt lgkmcnt(0)
	v_add_f32_e32 v11, v11, v32
	ds_bpermute_b32 v32, v6, v11
	s_waitcnt lgkmcnt(0)
	v_add_f32_e32 v11, v11, v32
	ds_bpermute_b32 v32, v7, v11
	s_waitcnt lgkmcnt(0)
	v_add_f32_e32 v11, v11, v32
	ds_bpermute_b32 v32, v8, v11
	s_waitcnt lgkmcnt(0)
	v_add_f32_e32 v11, v11, v32
	ds_bpermute_b32 v32, v9, v11
	s_waitcnt lgkmcnt(0)
	v_add_f32_e32 v11, v11, v32
	v_fmamk_f32 v11, v11, 0x3a800000, v10
	v_mul_f32_e32 v32, 0x4b800000, v11
	v_cmp_gt_f32_e32 vcc, s1, v11
	s_nop 1
	v_cndmask_b32_e32 v11, v11, v32, vcc
	v_rsq_f32_e32 v11, v11
	s_nop 0
	v_mul_f32_e32 v32, 0x45800000, v11
	v_cndmask_b32_e32 v32, v11, v32, vcc
	v_pk_mul_f32 v[12:13], v[32:33], v[12:13] op_sel_hi:[0,1]
	v_pk_mul_f32 v[14:15], v[32:33], v[14:15] op_sel_hi:[0,1]
	v_pk_mul_f32 v[14:15], v[14:15], v[30:31]
	v_pk_mul_f32 v[12:13], v[12:13], v[28:29]
	global_store_dwordx4 v[2:3], v[12:15], off offset:-2048
	v_pk_mul_f32 v[18:19], v[32:33], v[18:19] op_sel_hi:[0,1]
	v_pk_mul_f32 v[16:17], v[32:33], v[16:17] op_sel_hi:[0,1]
	v_pk_mul_f32 v[16:17], v[16:17], v[48:49]
	v_pk_mul_f32 v[18:19], v[18:19], v[50:51]
	global_store_dwordx4 v[2:3], v[16:19], off offset:-1024
	v_pk_mul_f32 v[26:27], v[32:33], v[26:27] op_sel_hi:[0,1]
	v_pk_mul_f32 v[24:25], v[32:33], v[24:25] op_sel_hi:[0,1]
	v_pk_mul_f32 v[24:25], v[24:25], v[52:53]
	v_pk_mul_f32 v[26:27], v[26:27], v[54:55]
	global_store_dwordx4 v[2:3], v[24:27], off
	v_pk_mul_f32 v[22:23], v[32:33], v[22:23] op_sel_hi:[0,1]
	v_pk_mul_f32 v[20:21], v[32:33], v[20:21] op_sel_hi:[0,1]
	v_pk_mul_f32 v[20:21], v[20:21], v[56:57]
	v_pk_mul_f32 v[22:23], v[22:23], v[58:59]
	global_store_dwordx4 v[2:3], v[20:23], off offset:1024
	v_lshl_add_u64 v[2:3], v[2:3], 0, s[2:3]
	s_cbranch_scc1 .LBB0_1360
